# compression-MLP K loop: operands staged through LDS by coalesced LDS-DMA (swizzled), A tile shared by 4 waves
# speedup vs baseline: 1.0612x; 1.0264x over previous
.LBB0_1356:
	v_readfirstlane_b32 s22, v32
	v_readfirstlane_b32 s23, v33
	v_readfirstlane_b32 s24, v30
	v_readfirstlane_b32 s25, v31
	s_sub_u32 s22, s22, 0x100
	s_subb_u32 s23, s23, 0
	s_sub_u32 s24, s24, 0x100
	s_subb_u32 s25, s25, 0
	v_and_b32_e32 v85, 63, v0
	v_lshrrev_b32_e32 v86, 3, v85
	v_and_b32_e32 v87, 7, v85
	v_xor_b32_e32 v87, v87, v86
	v_lshlrev_b32_e32 v87, 4, v87
	v_lshl_add_u32 v81, v86, 12, v87
	v_add_u32_e32 v82, 0x8000, v81
	v_add_u32_e32 v83, 0x10000, v81
	v_add_u32_e32 v84, 0x18000, v81
	s_lshl_b32 s4, s19, 9
	v_lshl_add_u32 v80, v86, 11, v87
	v_add_u32_e32 v80, s4, v80
	v_bfe_u32 v176, v0, 5, 1
	v_and_b32_e32 v85, 7, v18
	v_lshlrev_b32_e32 v86, 7, v18
	v_or_b32_e32 v87, 0, v176
	v_xor_b32_e32 v87, v87, v85
	v_lshl_add_u32 v172, v87, 4, v86
	v_or_b32_e32 v87, 2, v176
	v_xor_b32_e32 v87, v87, v85
	v_lshl_add_u32 v173, v87, 4, v86
	v_or_b32_e32 v87, 4, v176
	v_xor_b32_e32 v87, v87, v85
	v_lshl_add_u32 v174, v87, 4, v86
	v_or_b32_e32 v87, 6, v176
	v_xor_b32_e32 v87, v87, v85
	v_lshl_add_u32 v175, v87, 4, v86
	s_lshl_b32 s5, s21, 12
	s_lshl_b32 s98, s18, 12
	s_addk_i32 s98, 0x2000
	s_lshl_b32 s99, s19, 5
	s_add_i32 s99, s99, s5
	s_mov_b32 s100, s98
	s_add_i32 s4, s5, 0
	s_add_i32 s28, s98, 0
	v_add_u32_e32 v88, s4, v172
	v_add_u32_e32 v100, s28, v172
	v_add_u32_e32 v89, s4, v173
	v_add_u32_e32 v101, s28, v173
	v_add_u32_e32 v90, s4, v174
	v_add_u32_e32 v102, s28, v174
	v_add_u32_e32 v91, s4, v175
	v_add_u32_e32 v103, s28, v175
	s_add_i32 s4, s5, 40960
	s_add_i32 s28, s98, 40960
	v_add_u32_e32 v92, s4, v172
	v_add_u32_e32 v104, s28, v172
	v_add_u32_e32 v93, s4, v173
	v_add_u32_e32 v105, s28, v173
	v_add_u32_e32 v94, s4, v174
	v_add_u32_e32 v106, s28, v174
	v_add_u32_e32 v95, s4, v175
	v_add_u32_e32 v107, s28, v175
	s_add_i32 s4, s5, 81920
	s_add_i32 s28, s98, 81920
	v_add_u32_e32 v96, s4, v172
	v_add_u32_e32 v108, s28, v172
	v_add_u32_e32 v97, s4, v173
	v_add_u32_e32 v109, s28, v173
	v_add_u32_e32 v98, s4, v174
	v_add_u32_e32 v110, s28, v174
	v_add_u32_e32 v99, s4, v175
	v_add_u32_e32 v111, s28, v175
	s_add_i32 s101, s99, 0
	s_mov_b32 m0, s101
	s_add_i32 s101, s100, 0
	global_load_lds_dwordx4 v80, s[22:23]
	s_mov_b32 m0, s101
	s_add_i32 s101, s101, 0x400
	global_load_lds_dwordx4 v81, s[24:25]
	s_mov_b32 m0, s101
	s_add_i32 s101, s101, 0x400
	global_load_lds_dwordx4 v82, s[24:25]
	s_mov_b32 m0, s101
	s_add_i32 s101, s101, 0x400
	global_load_lds_dwordx4 v83, s[24:25]
	s_mov_b32 m0, s101
	s_nop 0
	global_load_lds_dwordx4 v84, s[24:25]
	s_add_u32 s22, s22, 0x80
	s_addc_u32 s23, s23, 0
	s_add_u32 s24, s24, 0x80
	s_addc_u32 s25, s25, 0
	s_add_i32 s101, s99, 40960
	s_mov_b32 m0, s101
	s_add_i32 s101, s100, 40960
	global_load_lds_dwordx4 v80, s[22:23]
	s_mov_b32 m0, s101
	s_add_i32 s101, s101, 0x400
	global_load_lds_dwordx4 v81, s[24:25]
	s_mov_b32 m0, s101
	s_add_i32 s101, s101, 0x400
	global_load_lds_dwordx4 v82, s[24:25]
	s_mov_b32 m0, s101
	s_add_i32 s101, s101, 0x400
	global_load_lds_dwordx4 v83, s[24:25]
	s_mov_b32 m0, s101
	s_nop 0
	global_load_lds_dwordx4 v84, s[24:25]
	s_add_u32 s22, s22, 0x80
	s_addc_u32 s23, s23, 0
	s_add_u32 s24, s24, 0x80
	s_addc_u32 s25, s25, 0
	s_waitcnt vmcnt(5)
	s_barrier
	s_add_i32 s101, s99, 81920
	s_mov_b32 m0, s101
	s_add_i32 s101, s100, 81920
	global_load_lds_dwordx4 v80, s[22:23]
	s_mov_b32 m0, s101
	s_add_i32 s101, s101, 0x400
	global_load_lds_dwordx4 v81, s[24:25]
	s_mov_b32 m0, s101
	s_add_i32 s101, s101, 0x400
	global_load_lds_dwordx4 v82, s[24:25]
	s_mov_b32 m0, s101
	s_add_i32 s101, s101, 0x400
	global_load_lds_dwordx4 v83, s[24:25]
	s_mov_b32 m0, s101
	s_nop 0
	global_load_lds_dwordx4 v84, s[24:25]
	s_add_u32 s22, s22, 0x80
	s_addc_u32 s23, s23, 0
	s_add_u32 s24, s24, 0x80
	s_addc_u32 s25, s25, 0
	ds_read_b128 v[140:143], v88
	ds_read_b128 v[144:147], v100
	ds_read_b128 v[148:151], v89
	ds_read_b128 v[152:155], v101
	ds_read_b128 v[156:159], v90
	ds_read_b128 v[160:163], v102
	ds_read_b128 v[164:167], v91
	ds_read_b128 v[168:171], v103
	s_waitcnt lgkmcnt(6)
	v_mfma_f32_32x32x16_bf16 v[2:17], v[140:143], v[144:147], v[2:17]
	s_waitcnt lgkmcnt(4)
	v_mfma_f32_32x32x16_bf16 v[2:17], v[148:151], v[152:155], v[2:17]
	s_waitcnt lgkmcnt(2)
	v_mfma_f32_32x32x16_bf16 v[2:17], v[156:159], v[160:163], v[2:17]
	s_waitcnt lgkmcnt(0)
	v_mfma_f32_32x32x16_bf16 v[2:17], v[164:167], v[168:171], v[2:17]
	s_waitcnt vmcnt(5)
	s_barrier
	s_add_i32 s101, s99, 0
	s_mov_b32 m0, s101
	s_add_i32 s101, s100, 0
	global_load_lds_dwordx4 v80, s[22:23]
	s_mov_b32 m0, s101
	s_add_i32 s101, s101, 0x400
	global_load_lds_dwordx4 v81, s[24:25]
	s_mov_b32 m0, s101
	s_add_i32 s101, s101, 0x400
	global_load_lds_dwordx4 v82, s[24:25]
	s_mov_b32 m0, s101
	s_add_i32 s101, s101, 0x400
	global_load_lds_dwordx4 v83, s[24:25]
	s_mov_b32 m0, s101
	s_nop 0
	global_load_lds_dwordx4 v84, s[24:25]
	s_add_u32 s22, s22, 0x80
	s_addc_u32 s23, s23, 0
	s_add_u32 s24, s24, 0x80
	s_addc_u32 s25, s25, 0
	ds_read_b128 v[140:143], v92
	ds_read_b128 v[144:147], v104
	ds_read_b128 v[148:151], v93
	ds_read_b128 v[152:155], v105
	ds_read_b128 v[156:159], v94
	ds_read_b128 v[160:163], v106
	ds_read_b128 v[164:167], v95
	ds_read_b128 v[168:171], v107
	s_waitcnt lgkmcnt(6)
	v_mfma_f32_32x32x16_bf16 v[2:17], v[140:143], v[144:147], v[2:17]
	s_waitcnt lgkmcnt(4)
	v_mfma_f32_32x32x16_bf16 v[2:17], v[148:151], v[152:155], v[2:17]
	s_waitcnt lgkmcnt(2)
	v_mfma_f32_32x32x16_bf16 v[2:17], v[156:159], v[160:163], v[2:17]
	s_waitcnt lgkmcnt(0)
	v_mfma_f32_32x32x16_bf16 v[2:17], v[164:167], v[168:171], v[2:17]
	s_waitcnt vmcnt(5)
	s_barrier
	s_add_i32 s101, s99, 40960
	s_mov_b32 m0, s101
	s_add_i32 s101, s100, 40960
	global_load_lds_dwordx4 v80, s[22:23]
	s_mov_b32 m0, s101
	s_add_i32 s101, s101, 0x400
	global_load_lds_dwordx4 v81, s[24:25]
	s_mov_b32 m0, s101
	s_add_i32 s101, s101, 0x400
	global_load_lds_dwordx4 v82, s[24:25]
	s_mov_b32 m0, s101
	s_add_i32 s101, s101, 0x400
	global_load_lds_dwordx4 v83, s[24:25]
	s_mov_b32 m0, s101
	s_nop 0
	global_load_lds_dwordx4 v84, s[24:25]
	s_add_u32 s22, s22, 0x80
	s_addc_u32 s23, s23, 0
	s_add_u32 s24, s24, 0x80
	s_addc_u32 s25, s25, 0
	ds_read_b128 v[140:143], v96
	ds_read_b128 v[144:147], v108
	ds_read_b128 v[148:151], v97
	ds_read_b128 v[152:155], v109
	ds_read_b128 v[156:159], v98
	ds_read_b128 v[160:163], v110
	ds_read_b128 v[164:167], v99
	ds_read_b128 v[168:171], v111
	s_waitcnt lgkmcnt(6)
	v_mfma_f32_32x32x16_bf16 v[2:17], v[140:143], v[144:147], v[2:17]
	s_waitcnt lgkmcnt(4)
	v_mfma_f32_32x32x16_bf16 v[2:17], v[148:151], v[152:155], v[2:17]
	s_waitcnt lgkmcnt(2)
	v_mfma_f32_32x32x16_bf16 v[2:17], v[156:159], v[160:163], v[2:17]
	s_waitcnt lgkmcnt(0)
	v_mfma_f32_32x32x16_bf16 v[2:17], v[164:167], v[168:171], v[2:17]
	s_waitcnt vmcnt(5)
	s_barrier
	s_add_i32 s101, s99, 81920
	s_mov_b32 m0, s101
	s_add_i32 s101, s100, 81920
	global_load_lds_dwordx4 v80, s[22:23]
	s_mov_b32 m0, s101
	s_add_i32 s101, s101, 0x400
	global_load_lds_dwordx4 v81, s[24:25]
	s_mov_b32 m0, s101
	s_add_i32 s101, s101, 0x400
	global_load_lds_dwordx4 v82, s[24:25]
	s_mov_b32 m0, s101
	s_add_i32 s101, s101, 0x400
	global_load_lds_dwordx4 v83, s[24:25]
	s_mov_b32 m0, s101
	s_nop 0
	global_load_lds_dwordx4 v84, s[24:25]
	s_add_u32 s22, s22, 0x80
	s_addc_u32 s23, s23, 0
	s_add_u32 s24, s24, 0x80
	s_addc_u32 s25, s25, 0
	ds_read_b128 v[140:143], v88
	ds_read_b128 v[144:147], v100
	ds_read_b128 v[148:151], v89
	ds_read_b128 v[152:155], v101
	ds_read_b128 v[156:159], v90
	ds_read_b128 v[160:163], v102
	ds_read_b128 v[164:167], v91
	ds_read_b128 v[168:171], v103
	s_waitcnt lgkmcnt(6)
	v_mfma_f32_32x32x16_bf16 v[2:17], v[140:143], v[144:147], v[2:17]
	s_waitcnt lgkmcnt(4)
	v_mfma_f32_32x32x16_bf16 v[2:17], v[148:151], v[152:155], v[2:17]
	s_waitcnt lgkmcnt(2)
	v_mfma_f32_32x32x16_bf16 v[2:17], v[156:159], v[160:163], v[2:17]
	s_waitcnt lgkmcnt(0)
	v_mfma_f32_32x32x16_bf16 v[2:17], v[164:167], v[168:171], v[2:17]
	s_waitcnt vmcnt(5)
	s_barrier
	s_add_i32 s101, s99, 0
	s_mov_b32 m0, s101
	s_add_i32 s101, s100, 0
	global_load_lds_dwordx4 v80, s[22:23]
	s_mov_b32 m0, s101
	s_add_i32 s101, s101, 0x400
	global_load_lds_dwordx4 v81, s[24:25]
	s_mov_b32 m0, s101
	s_add_i32 s101, s101, 0x400
	global_load_lds_dwordx4 v82, s[24:25]
	s_mov_b32 m0, s101
	s_add_i32 s101, s101, 0x400
	global_load_lds_dwordx4 v83, s[24:25]
	s_mov_b32 m0, s101
	s_nop 0
	global_load_lds_dwordx4 v84, s[24:25]
	s_add_u32 s22, s22, 0x80
	s_addc_u32 s23, s23, 0
	s_add_u32 s24, s24, 0x80
	s_addc_u32 s25, s25, 0
	ds_read_b128 v[140:143], v92
	ds_read_b128 v[144:147], v104
	ds_read_b128 v[148:151], v93
	ds_read_b128 v[152:155], v105
	ds_read_b128 v[156:159], v94
	ds_read_b128 v[160:163], v106
	ds_read_b128 v[164:167], v95
	ds_read_b128 v[168:171], v107
	s_waitcnt lgkmcnt(6)
	v_mfma_f32_32x32x16_bf16 v[2:17], v[140:143], v[144:147], v[2:17]
	s_waitcnt lgkmcnt(4)
	v_mfma_f32_32x32x16_bf16 v[2:17], v[148:151], v[152:155], v[2:17]
	s_waitcnt lgkmcnt(2)
	v_mfma_f32_32x32x16_bf16 v[2:17], v[156:159], v[160:163], v[2:17]
	s_waitcnt lgkmcnt(0)
	v_mfma_f32_32x32x16_bf16 v[2:17], v[164:167], v[168:171], v[2:17]
	s_waitcnt vmcnt(5)
	s_barrier
	s_add_i32 s101, s99, 40960
	s_mov_b32 m0, s101
	s_add_i32 s101, s100, 40960
	global_load_lds_dwordx4 v80, s[22:23]
	s_mov_b32 m0, s101
	s_add_i32 s101, s101, 0x400
	global_load_lds_dwordx4 v81, s[24:25]
	s_mov_b32 m0, s101
	s_add_i32 s101, s101, 0x400
	global_load_lds_dwordx4 v82, s[24:25]
	s_mov_b32 m0, s101
	s_add_i32 s101, s101, 0x400
	global_load_lds_dwordx4 v83, s[24:25]
	s_mov_b32 m0, s101
	s_nop 0
	global_load_lds_dwordx4 v84, s[24:25]
	s_add_u32 s22, s22, 0x80
	s_addc_u32 s23, s23, 0
	s_add_u32 s24, s24, 0x80
	s_addc_u32 s25, s25, 0
	ds_read_b128 v[140:143], v96
	ds_read_b128 v[144:147], v108
	ds_read_b128 v[148:151], v97
	ds_read_b128 v[152:155], v109
	ds_read_b128 v[156:159], v98
	ds_read_b128 v[160:163], v110
	ds_read_b128 v[164:167], v99
	ds_read_b128 v[168:171], v111
	s_waitcnt lgkmcnt(6)
	v_mfma_f32_32x32x16_bf16 v[2:17], v[140:143], v[144:147], v[2:17]
	s_waitcnt lgkmcnt(4)
	v_mfma_f32_32x32x16_bf16 v[2:17], v[148:151], v[152:155], v[2:17]
	s_waitcnt lgkmcnt(2)
	v_mfma_f32_32x32x16_bf16 v[2:17], v[156:159], v[160:163], v[2:17]
	s_waitcnt lgkmcnt(0)
	v_mfma_f32_32x32x16_bf16 v[2:17], v[164:167], v[168:171], v[2:17]
	s_waitcnt vmcnt(5)
	s_barrier
	s_add_i32 s101, s99, 81920
	s_mov_b32 m0, s101
	s_add_i32 s101, s100, 81920
	global_load_lds_dwordx4 v80, s[22:23]
	s_mov_b32 m0, s101
	s_add_i32 s101, s101, 0x400
	global_load_lds_dwordx4 v81, s[24:25]
	s_mov_b32 m0, s101
	s_add_i32 s101, s101, 0x400
	global_load_lds_dwordx4 v82, s[24:25]
	s_mov_b32 m0, s101
	s_add_i32 s101, s101, 0x400
	global_load_lds_dwordx4 v83, s[24:25]
	s_mov_b32 m0, s101
	s_nop 0
	global_load_lds_dwordx4 v84, s[24:25]
	s_add_u32 s22, s22, 0x80
	s_addc_u32 s23, s23, 0
	s_add_u32 s24, s24, 0x80
	s_addc_u32 s25, s25, 0
	ds_read_b128 v[140:143], v88
	ds_read_b128 v[144:147], v100
	ds_read_b128 v[148:151], v89
	ds_read_b128 v[152:155], v101
	ds_read_b128 v[156:159], v90
	ds_read_b128 v[160:163], v102
	ds_read_b128 v[164:167], v91
	ds_read_b128 v[168:171], v103
	s_waitcnt lgkmcnt(6)
	v_mfma_f32_32x32x16_bf16 v[2:17], v[140:143], v[144:147], v[2:17]
	s_waitcnt lgkmcnt(4)
	v_mfma_f32_32x32x16_bf16 v[2:17], v[148:151], v[152:155], v[2:17]
	s_waitcnt lgkmcnt(2)
	v_mfma_f32_32x32x16_bf16 v[2:17], v[156:159], v[160:163], v[2:17]
	s_waitcnt lgkmcnt(0)
	v_mfma_f32_32x32x16_bf16 v[2:17], v[164:167], v[168:171], v[2:17]
	s_waitcnt vmcnt(5)
	s_barrier
	s_add_i32 s101, s99, 0
	s_mov_b32 m0, s101
	s_add_i32 s101, s100, 0
	global_load_lds_dwordx4 v80, s[22:23]
	s_mov_b32 m0, s101
	s_add_i32 s101, s101, 0x400
	global_load_lds_dwordx4 v81, s[24:25]
	s_mov_b32 m0, s101
	s_add_i32 s101, s101, 0x400
	global_load_lds_dwordx4 v82, s[24:25]
	s_mov_b32 m0, s101
	s_add_i32 s101, s101, 0x400
	global_load_lds_dwordx4 v83, s[24:25]
	s_mov_b32 m0, s101
	s_nop 0
	global_load_lds_dwordx4 v84, s[24:25]
	s_add_u32 s22, s22, 0x80
	s_addc_u32 s23, s23, 0
	s_add_u32 s24, s24, 0x80
	s_addc_u32 s25, s25, 0
	ds_read_b128 v[140:143], v92
	ds_read_b128 v[144:147], v104
	ds_read_b128 v[148:151], v93
	ds_read_b128 v[152:155], v105
	ds_read_b128 v[156:159], v94
	ds_read_b128 v[160:163], v106
	ds_read_b128 v[164:167], v95
	ds_read_b128 v[168:171], v107
	s_waitcnt lgkmcnt(6)
	v_mfma_f32_32x32x16_bf16 v[2:17], v[140:143], v[144:147], v[2:17]
	s_waitcnt lgkmcnt(4)
	v_mfma_f32_32x32x16_bf16 v[2:17], v[148:151], v[152:155], v[2:17]
	s_waitcnt lgkmcnt(2)
	v_mfma_f32_32x32x16_bf16 v[2:17], v[156:159], v[160:163], v[2:17]
	s_waitcnt lgkmcnt(0)
	v_mfma_f32_32x32x16_bf16 v[2:17], v[164:167], v[168:171], v[2:17]
	s_waitcnt vmcnt(5)
	s_barrier
	s_add_i32 s101, s99, 40960
	s_mov_b32 m0, s101
	s_add_i32 s101, s100, 40960
	global_load_lds_dwordx4 v80, s[22:23]
	s_mov_b32 m0, s101
	s_add_i32 s101, s101, 0x400
	global_load_lds_dwordx4 v81, s[24:25]
	s_mov_b32 m0, s101
	s_add_i32 s101, s101, 0x400
	global_load_lds_dwordx4 v82, s[24:25]
	s_mov_b32 m0, s101
	s_add_i32 s101, s101, 0x400
	global_load_lds_dwordx4 v83, s[24:25]
	s_mov_b32 m0, s101
	s_nop 0
	global_load_lds_dwordx4 v84, s[24:25]
	s_add_u32 s22, s22, 0x80
	s_addc_u32 s23, s23, 0
	s_add_u32 s24, s24, 0x80
	s_addc_u32 s25, s25, 0
	ds_read_b128 v[140:143], v96
	ds_read_b128 v[144:147], v108
	ds_read_b128 v[148:151], v97
	ds_read_b128 v[152:155], v109
	ds_read_b128 v[156:159], v98
	ds_read_b128 v[160:163], v110
	ds_read_b128 v[164:167], v99
	ds_read_b128 v[168:171], v111
	s_waitcnt lgkmcnt(6)
	v_mfma_f32_32x32x16_bf16 v[2:17], v[140:143], v[144:147], v[2:17]
	s_waitcnt lgkmcnt(4)
	v_mfma_f32_32x32x16_bf16 v[2:17], v[148:151], v[152:155], v[2:17]
	s_waitcnt lgkmcnt(2)
	v_mfma_f32_32x32x16_bf16 v[2:17], v[156:159], v[160:163], v[2:17]
	s_waitcnt lgkmcnt(0)
	v_mfma_f32_32x32x16_bf16 v[2:17], v[164:167], v[168:171], v[2:17]
	s_waitcnt vmcnt(5)
	s_barrier
	s_add_i32 s101, s99, 81920
	s_mov_b32 m0, s101
	s_add_i32 s101, s100, 81920
	global_load_lds_dwordx4 v80, s[22:23]
	s_mov_b32 m0, s101
	s_add_i32 s101, s101, 0x400
	global_load_lds_dwordx4 v81, s[24:25]
	s_mov_b32 m0, s101
	s_add_i32 s101, s101, 0x400
	global_load_lds_dwordx4 v82, s[24:25]
	s_mov_b32 m0, s101
	s_add_i32 s101, s101, 0x400
	global_load_lds_dwordx4 v83, s[24:25]
	s_mov_b32 m0, s101
	s_nop 0
	global_load_lds_dwordx4 v84, s[24:25]
	s_add_u32 s22, s22, 0x80
	s_addc_u32 s23, s23, 0
	s_add_u32 s24, s24, 0x80
	s_addc_u32 s25, s25, 0
	ds_read_b128 v[140:143], v88
	ds_read_b128 v[144:147], v100
	ds_read_b128 v[148:151], v89
	ds_read_b128 v[152:155], v101
	ds_read_b128 v[156:159], v90
	ds_read_b128 v[160:163], v102
	ds_read_b128 v[164:167], v91
	ds_read_b128 v[168:171], v103
	s_waitcnt lgkmcnt(6)
	v_mfma_f32_32x32x16_bf16 v[2:17], v[140:143], v[144:147], v[2:17]
	s_waitcnt lgkmcnt(4)
	v_mfma_f32_32x32x16_bf16 v[2:17], v[148:151], v[152:155], v[2:17]
	s_waitcnt lgkmcnt(2)
	v_mfma_f32_32x32x16_bf16 v[2:17], v[156:159], v[160:163], v[2:17]
	s_waitcnt lgkmcnt(0)
	v_mfma_f32_32x32x16_bf16 v[2:17], v[164:167], v[168:171], v[2:17]
	s_waitcnt vmcnt(5)
	s_barrier
	s_add_i32 s101, s99, 0
	s_mov_b32 m0, s101
	s_add_i32 s101, s100, 0
	global_load_lds_dwordx4 v80, s[22:23]
	s_mov_b32 m0, s101
	s_add_i32 s101, s101, 0x400
	global_load_lds_dwordx4 v81, s[24:25]
	s_mov_b32 m0, s101
	s_add_i32 s101, s101, 0x400
	global_load_lds_dwordx4 v82, s[24:25]
	s_mov_b32 m0, s101
	s_add_i32 s101, s101, 0x400
	global_load_lds_dwordx4 v83, s[24:25]
	s_mov_b32 m0, s101
	s_nop 0
	global_load_lds_dwordx4 v84, s[24:25]
	s_add_u32 s22, s22, 0x80
	s_addc_u32 s23, s23, 0
	s_add_u32 s24, s24, 0x80
	s_addc_u32 s25, s25, 0
	ds_read_b128 v[140:143], v92
	ds_read_b128 v[144:147], v104
	ds_read_b128 v[148:151], v93
	ds_read_b128 v[152:155], v105
	ds_read_b128 v[156:159], v94
	ds_read_b128 v[160:163], v106
	ds_read_b128 v[164:167], v95
	ds_read_b128 v[168:171], v107
	s_waitcnt lgkmcnt(6)
	v_mfma_f32_32x32x16_bf16 v[2:17], v[140:143], v[144:147], v[2:17]
	s_waitcnt lgkmcnt(4)
	v_mfma_f32_32x32x16_bf16 v[2:17], v[148:151], v[152:155], v[2:17]
	s_waitcnt lgkmcnt(2)
	v_mfma_f32_32x32x16_bf16 v[2:17], v[156:159], v[160:163], v[2:17]
	s_waitcnt lgkmcnt(0)
	v_mfma_f32_32x32x16_bf16 v[2:17], v[164:167], v[168:171], v[2:17]
	s_waitcnt vmcnt(5)
	s_barrier
	s_add_i32 s101, s99, 40960
	s_mov_b32 m0, s101
	s_add_i32 s101, s100, 40960
	global_load_lds_dwordx4 v80, s[22:23]
	s_mov_b32 m0, s101
	s_add_i32 s101, s101, 0x400
	global_load_lds_dwordx4 v81, s[24:25]
	s_mov_b32 m0, s101
	s_add_i32 s101, s101, 0x400
	global_load_lds_dwordx4 v82, s[24:25]
	s_mov_b32 m0, s101
	s_add_i32 s101, s101, 0x400
	global_load_lds_dwordx4 v83, s[24:25]
	s_mov_b32 m0, s101
	s_nop 0
	global_load_lds_dwordx4 v84, s[24:25]
	s_add_u32 s22, s22, 0x80
	s_addc_u32 s23, s23, 0
	s_add_u32 s24, s24, 0x80
	s_addc_u32 s25, s25, 0
	ds_read_b128 v[140:143], v96
	ds_read_b128 v[144:147], v108
	ds_read_b128 v[148:151], v97
	ds_read_b128 v[152:155], v109
	ds_read_b128 v[156:159], v98
	ds_read_b128 v[160:163], v110
	ds_read_b128 v[164:167], v99
	ds_read_b128 v[168:171], v111
	s_waitcnt lgkmcnt(6)
	v_mfma_f32_32x32x16_bf16 v[2:17], v[140:143], v[144:147], v[2:17]
	s_waitcnt lgkmcnt(4)
	v_mfma_f32_32x32x16_bf16 v[2:17], v[148:151], v[152:155], v[2:17]
	s_waitcnt lgkmcnt(2)
	v_mfma_f32_32x32x16_bf16 v[2:17], v[156:159], v[160:163], v[2:17]
	s_waitcnt lgkmcnt(0)
	v_mfma_f32_32x32x16_bf16 v[2:17], v[164:167], v[168:171], v[2:17]
	s_waitcnt vmcnt(5)
	s_barrier
	s_add_i32 s101, s99, 81920
	s_mov_b32 m0, s101
	s_add_i32 s101, s100, 81920
	global_load_lds_dwordx4 v80, s[22:23]
	s_mov_b32 m0, s101
	s_add_i32 s101, s101, 0x400
	global_load_lds_dwordx4 v81, s[24:25]
	s_mov_b32 m0, s101
	s_add_i32 s101, s101, 0x400
	global_load_lds_dwordx4 v82, s[24:25]
	s_mov_b32 m0, s101
	s_add_i32 s101, s101, 0x400
	global_load_lds_dwordx4 v83, s[24:25]
	s_mov_b32 m0, s101
	s_nop 0
	global_load_lds_dwordx4 v84, s[24:25]
	s_add_u32 s22, s22, 0x80
	s_addc_u32 s23, s23, 0
	s_add_u32 s24, s24, 0x80
	s_addc_u32 s25, s25, 0
	ds_read_b128 v[140:143], v88
	ds_read_b128 v[144:147], v100
	ds_read_b128 v[148:151], v89
	ds_read_b128 v[152:155], v101
	ds_read_b128 v[156:159], v90
	ds_read_b128 v[160:163], v102
	ds_read_b128 v[164:167], v91
	ds_read_b128 v[168:171], v103
	s_waitcnt lgkmcnt(6)
	v_mfma_f32_32x32x16_bf16 v[2:17], v[140:143], v[144:147], v[2:17]
	s_waitcnt lgkmcnt(4)
	v_mfma_f32_32x32x16_bf16 v[2:17], v[148:151], v[152:155], v[2:17]
	s_waitcnt lgkmcnt(2)
	v_mfma_f32_32x32x16_bf16 v[2:17], v[156:159], v[160:163], v[2:17]
	s_waitcnt lgkmcnt(0)
	v_mfma_f32_32x32x16_bf16 v[2:17], v[164:167], v[168:171], v[2:17]
	s_waitcnt vmcnt(5)
	s_barrier
	s_add_i32 s101, s99, 0
	s_mov_b32 m0, s101
	s_add_i32 s101, s100, 0
	global_load_lds_dwordx4 v80, s[22:23]
	s_mov_b32 m0, s101
	s_add_i32 s101, s101, 0x400
	global_load_lds_dwordx4 v81, s[24:25]
	s_mov_b32 m0, s101
	s_add_i32 s101, s101, 0x400
	global_load_lds_dwordx4 v82, s[24:25]
	s_mov_b32 m0, s101
	s_add_i32 s101, s101, 0x400
	global_load_lds_dwordx4 v83, s[24:25]
	s_mov_b32 m0, s101
	s_nop 0
	global_load_lds_dwordx4 v84, s[24:25]
	s_add_u32 s22, s22, 0x80
	s_addc_u32 s23, s23, 0
	s_add_u32 s24, s24, 0x80
	s_addc_u32 s25, s25, 0
	ds_read_b128 v[140:143], v92
	ds_read_b128 v[144:147], v104
	ds_read_b128 v[148:151], v93
	ds_read_b128 v[152:155], v105
	ds_read_b128 v[156:159], v94
	ds_read_b128 v[160:163], v106
	ds_read_b128 v[164:167], v95
	ds_read_b128 v[168:171], v107
	s_waitcnt lgkmcnt(6)
	v_mfma_f32_32x32x16_bf16 v[2:17], v[140:143], v[144:147], v[2:17]
	s_waitcnt lgkmcnt(4)
	v_mfma_f32_32x32x16_bf16 v[2:17], v[148:151], v[152:155], v[2:17]
	s_waitcnt lgkmcnt(2)
	v_mfma_f32_32x32x16_bf16 v[2:17], v[156:159], v[160:163], v[2:17]
	s_waitcnt lgkmcnt(0)
	v_mfma_f32_32x32x16_bf16 v[2:17], v[164:167], v[168:171], v[2:17]
	s_waitcnt vmcnt(5)
	s_barrier
	ds_read_b128 v[140:143], v96
	ds_read_b128 v[144:147], v108
	ds_read_b128 v[148:151], v97
	ds_read_b128 v[152:155], v109
	ds_read_b128 v[156:159], v98
	ds_read_b128 v[160:163], v110
	ds_read_b128 v[164:167], v99
	ds_read_b128 v[168:171], v111
	s_waitcnt lgkmcnt(6)
	v_mfma_f32_32x32x16_bf16 v[2:17], v[140:143], v[144:147], v[2:17]
	s_waitcnt lgkmcnt(4)
	v_mfma_f32_32x32x16_bf16 v[2:17], v[148:151], v[152:155], v[2:17]
	s_waitcnt lgkmcnt(2)
	v_mfma_f32_32x32x16_bf16 v[2:17], v[156:159], v[160:163], v[2:17]
	s_waitcnt lgkmcnt(0)
	v_mfma_f32_32x32x16_bf16 v[2:17], v[164:167], v[168:171], v[2:17]
	s_waitcnt vmcnt(0)
	s_barrier
	ds_read_b128 v[140:143], v88
	ds_read_b128 v[144:147], v100
	ds_read_b128 v[148:151], v89
	ds_read_b128 v[152:155], v101
	ds_read_b128 v[156:159], v90
	ds_read_b128 v[160:163], v102
	ds_read_b128 v[164:167], v91
	ds_read_b128 v[168:171], v103
	s_waitcnt lgkmcnt(6)
	v_mfma_f32_32x32x16_bf16 v[2:17], v[140:143], v[144:147], v[2:17]
	s_waitcnt lgkmcnt(4)
	v_mfma_f32_32x32x16_bf16 v[2:17], v[148:151], v[152:155], v[2:17]
	s_waitcnt lgkmcnt(2)
	v_mfma_f32_32x32x16_bf16 v[2:17], v[156:159], v[160:163], v[2:17]
	s_waitcnt lgkmcnt(0)
	v_mfma_f32_32x32x16_bf16 v[2:17], v[164:167], v[168:171], v[2:17]
	s_barrier
	s_cmp_lg_u32 s21, 1
	s_cbranch_scc1 .LBB0_1359
	v_lshl_add_u32 v20, s19, 2, v34
	s_nop 7
	ds_write2st64_b32 v20, v2, v3 offset1:2
	ds_write2st64_b32 v20, v4, v5 offset0:4 offset1:6
	ds_write2st64_b32 v20, v6, v7 offset0:16 offset1:18
	ds_write2st64_b32 v20, v8, v9 offset0:20 offset1:22
	ds_write2st64_b32 v20, v10, v11 offset0:32 offset1:34
	ds_write2st64_b32 v20, v12, v13 offset0:36 offset1:38
	ds_write2st64_b32 v20, v14, v15 offset0:48 offset1:50
	ds_write2st64_b32 v20, v16, v17 offset0:52 offset1:54

	.amdhsa_kernel _Z6mk_fwd4Args
		.amdhsa_group_segment_fixed_size 0
		.amdhsa_private_segment_fixed_size 0
		.amdhsa_kernarg_size 416
		.amdhsa_user_sgpr_count 2
		.amdhsa_user_sgpr_dispatch_ptr 0
		.amdhsa_user_sgpr_queue_ptr 0
		.amdhsa_user_sgpr_kernarg_segment_ptr 1
		.amdhsa_user_sgpr_dispatch_id 0
		.amdhsa_user_sgpr_kernarg_preload_length 0
		.amdhsa_user_sgpr_kernarg_preload_offset 0
		.amdhsa_user_sgpr_private_segment_size 0
		.amdhsa_uses_dynamic_stack 0
		.amdhsa_enable_private_segment 0
		.amdhsa_system_sgpr_workgroup_id_x 1
		.amdhsa_system_sgpr_workgroup_id_y 0
		.amdhsa_system_sgpr_workgroup_id_z 0
		.amdhsa_system_sgpr_workgroup_info 0
		.amdhsa_system_vgpr_workitem_id 0
		.amdhsa_next_free_vgpr 254
		.amdhsa_next_free_sgpr 102
		.amdhsa_accum_offset 256
		.amdhsa_reserve_vcc 1
		.amdhsa_float_round_mode_32 0
		.amdhsa_float_round_mode_16_64 0
		.amdhsa_float_denorm_mode_32 3
		.amdhsa_float_denorm_mode_16_64 3
		.amdhsa_dx10_clamp 1
		.amdhsa_ieee_mode 1
		.amdhsa_fp16_overflow 0
		.amdhsa_tg_split 0
		.amdhsa_exception_fp_ieee_invalid_op 0
		.amdhsa_exception_fp_denorm_src 0
		.amdhsa_exception_fp_ieee_div_zero 0
		.amdhsa_exception_fp_ieee_overflow 0
		.amdhsa_exception_fp_ieee_underflow 0
		.amdhsa_exception_fp_ieee_inexact 0
		.amdhsa_exception_int_div_zero 0
	.end_amdhsa_kernel

amdhsa.kernels:
  - .agpr_count:     0
    .args:
      - .offset:         0
        .size:           160
        .value_kind:     by_value
      - .offset:         160
        .size:           4
        .value_kind:     hidden_block_count_x
      - .offset:         164
        .size:           4
        .value_kind:     hidden_block_count_y
      - .offset:         168
        .size:           4
        .value_kind:     hidden_block_count_z
      - .offset:         172
        .size:           2
        .value_kind:     hidden_group_size_x
      - .offset:         174
        .size:           2
        .value_kind:     hidden_group_size_y
      - .offset:         176
        .size:           2
        .value_kind:     hidden_group_size_z
      - .offset:         178
        .size:           2
        .value_kind:     hidden_remainder_x
      - .offset:         180
        .size:           2
        .value_kind:     hidden_remainder_y
      - .offset:         182
        .size:           2
        .value_kind:     hidden_remainder_z
      - .offset:         200
        .size:           8
        .value_kind:     hidden_global_offset_x
      - .offset:         208
        .size:           8
        .value_kind:     hidden_global_offset_y
      - .offset:         216
        .size:           8
        .value_kind:     hidden_global_offset_z
      - .offset:         224
        .size:           2
        .value_kind:     hidden_grid_dims
      - .offset:         280
        .size:           4
        .value_kind:     hidden_dynamic_lds_size
    .group_segment_fixed_size: 0
    .kernarg_segment_align: 8
    .kernarg_segment_size: 416
    .language:       OpenCL C
    .language_version:
      - 2
      - 0
    .max_flat_workgroup_size: 512
    .name:           _Z6mk_fwd4Args
    .private_segment_fixed_size: 0
    .sgpr_count:     108
    .sgpr_spill_count: 50
    .symbol:         _Z6mk_fwd4Args.kd
    .uniform_work_group_size: 1
    .uses_dynamic_stack: false
    .vgpr_count:     254
    .vgpr_spill_count: 0
    .wavefront_size: 64
